# v28 + FFN-in fast path alternates two C staging buffers per quadrant so the pre-write barrier is dropped (one barrier per quadrant, writes stay after compute)
# baseline (speedup 1.0000x reference)
; template <int MODE>
; DI void gemm_epilogue(const float* Cs, int m0, int n0, const Epi& ep) {
;     ...
;     } else if (MODE == 4) {
;         const int mt = m0 >> 7, ch0 = (n0 >> 7) * 64, c8 = (tid & 7) * 8, ch = ch0 + c8;
;         const float* cw = ep.c0;
;         const F8 w0 = ldf8(cw + ch), w1 = ldf8(cw + 2816 + ch), w2 = ldf8(cw + 2 * 2816 + ch);
;         const bool defer01 = (m0 < MP) && ((m0 & 8191) != 0);
; #pragma unroll
;         for (int it = 0; it < 2; ++it) {
;             const int i = (tid >> 3) + 64 * it, r = m0 + i;
;             int sq, pos, len; rowinfo(r, sq, pos, len);
;             const F8 g0 = ldf8(Cs + i * LDC + c8), up = ldf8(Cs + i * LDC + 64 + c8);
;             if (i >= 126) stf8(ep.f0 + ((size_t)mt * 2 + (i - 126)) * 2816 + ch, g0);
;             if (i < 2) { stf8(ep.f1 + ((size_t)mt * 2 + i) * 2816 + ch, g0); stf8(ep.f2 + ((size_t)mt * 2 + i) * 2816 + ch, up); }
;             if (pos >= len - 2) {
;                 float* so = sq < 4 ? ep.out + O_PFF + (((size_t)ep.layer * 4 + sq) * 2 + (pos - (len - 2))) * 2816
;                                    : ep.out + O_SFF + (((size_t)ep.layer * 8 + (sq - 4)) * 2 + (pos - (len - 2))) * 2816;
;                 stf8(so + ch, g0);
;             }
;             if (i < 2 && defer01) continue;
;             F8 g1, g2;
;             const float* hist = sq >= 4 ? ep.c1 + ((size_t)ep.layer * 8 + (sq - 4)) * 2 * 2816 + ch : nullptr;
;             if (pos >= 1) g1 = ldf8(Cs + (i - 1) * LDC + c8);
;             else if (hist) g1 = ldf8(hist + 2816);
;             else { for (int e = 0; e < 8; ++e) g1.v[e] = 0.f; }
;             if (pos >= 2) g2 = ldf8(Cs + (i - 2) * LDC + c8);
; template <int MODE>
; DI void gemm_phase(const bf16_t* __restrict__ A, const bf16_t* __restrict__ Bt, int M, int N, int K, const Epi& ep) {
;     ...
; #pragma unroll
;         for (int ai = 0; ai < 2; ++ai)
; #pragma unroll
;             for (int bj = 0; bj < 2; ++bj) {
; #pragma unroll
;                 for (int m = 0; m < 4; ++m)
; #pragma unroll
;                     for (int n = 0; n < 2; ++n)
;                         *(f32x4*)(Cs + (wr * 64 + m * 16 + fr) * LDC + wc * 32 + n * 16 + fq * 4) = acc[ai][bj][m][n];
;                 __syncthreads();
;                 gemm_epilogue<MODE>(Cs, brow + ai * 128, bcol + bj * 128, ep);
.Lffn_fast:
	s_lshl_b32 s54, s27, 8
	s_lshl_b32 s30, s26, 7
	s_lshl_b32 s31, s27, 2
	v_bfe_u32 v64, v250, 2, 3
	v_mov_b32_e32 v65, 0x31130220
	v_lshlrev_b32_e32 v64, 2, v64
	v_bfe_u32 v66, v250, 5, 1
	v_lshrrev_b32_e32 v195, 6, v250
	v_lshrrev_b32_e32 v65, v64, v65
	v_lshlrev_b32_e32 v195, 3, v195
	v_and_b32_e32 v65, 3, v65
	v_lshl_add_u32 v195, v66, 2, v195
	v_bfe_u32 v212, v250, 3, 1
	v_add_u32_e32 v195, v195, v65
	v_and_b32_e32 v67, 3, v250
	v_lshlrev_b32_e32 v212, 5, v212
	v_lshl_or_b32 v212, v67, 3, v212
	v_add_u32_e32 v64, s30, v212
	v_add_u32_e32 v65, s54, v195
	s_movk_i32 s0, 0x1600
	v_add_u32_e32 v66, s31, v195
	v_mul_lo_u32 v65, v65, s0
	v_mul_lo_u32 v66, v66, s3
	v_mul_u32_u24_e32 v197, 0x210, v195
	v_lshl_add_u32 v65, v64, 1, v65
	v_lshlrev_b32_e32 v64, 2, v64
	v_lshl_add_u32 v67, v212, 2, 16
	v_add_u32_e32 v66, v66, v64
	v_add_u32_e32 v197, v197, v67
	v_cmp_lt_u32_e64 s[40:41], 1, v195
	v_cmp_gt_u32_e64 s[42:43], 2, v195
	v_cmp_lt_u32_e64 s[44:45], 61, v195
	v_add_u32_e32 v196, 0xfffffbe0, v197
	v_max_i32_e32 v196, v196, v67
	v_add_u32_e32 v156, 0x10800, v194
	v_add_u32_e32 v157, 0x10800, v196
	v_add_u32_e32 v158, 0x10800, v197
	s_mov_b32 s30, 0xbfb8aa3b
	s_mov_b32 s31, 0xbfb8aa3b
	global_load_dwordx4 v[128:131], v64, s[6:7] offset:0
	global_load_dwordx4 v[132:135], v64, s[6:7] offset:16
	global_load_dwordx4 v[136:139], v64, s[14:15] offset:0
	global_load_dwordx4 v[140:143], v64, s[14:15] offset:16
	global_load_dwordx4 v[144:147], v64, s[18:19] offset:0
	global_load_dwordx4 v[148:151], v64, s[18:19] offset:16
	ds_write_b128 v194, v[96:99]
	ds_write_b128 v194, v[100:103] offset:64
	ds_write_b128 v194, v[104:107] offset:8448
	ds_write_b128 v194, v[108:111] offset:8512
	ds_write_b128 v194, v[112:115] offset:16896
	ds_write_b128 v194, v[116:119] offset:16960
	ds_write_b128 v194, v[120:123] offset:25344
	ds_write_b128 v194, v[124:127] offset:25408
	s_waitcnt lgkmcnt(0)
	s_barrier
	ds_read_b128 v[96:99], v197
	ds_read_b128 v[100:103], v197 offset:16
	ds_read_b128 v[104:107], v197 offset:256
	ds_read_b128 v[108:111], v197 offset:272
	ds_read_b128 v[112:115], v196 offset:528
	ds_read_b128 v[116:119], v196 offset:544
	ds_read_b128 v[120:123], v196
	ds_read_b128 v[124:127], v196 offset:16
	s_waitcnt vmcnt(0)
	s_mov_b64 exec, s[42:43]
	s_cbranch_execz .Lffn_f1
	s_waitcnt lgkmcnt(4)
	global_store_dwordx4 v66, v[96:99], s[80:81] offset:0
	global_store_dwordx4 v66, v[100:103], s[80:81] offset:16
	global_store_dwordx4 v66, v[104:107], s[82:83] offset:0
	global_store_dwordx4 v66, v[108:111], s[82:83] offset:16

; template <int MODE>
; DI void gemm_epilogue(const float* Cs, int m0, int n0, const Epi& ep) {
;     ...
;         const F8 w0 = ldf8(cw + ch), w1 = ldf8(cw + 2816 + ch), w2 = ldf8(cw + 2 * 2816 + ch);
;         const bool defer01 = (m0 < MP) && ((m0 & 8191) != 0);
; #pragma unroll
;         for (int it = 0; it < 2; ++it) {
;             const int i = (tid >> 3) + 64 * it, r = m0 + i;
;             int sq, pos, len; rowinfo(r, sq, pos, len);
;             const F8 g0 = ldf8(Cs + i * LDC + c8), up = ldf8(Cs + i * LDC + 64 + c8);
;             if (i >= 126) stf8(ep.f0 + ((size_t)mt * 2 + (i - 126)) * 2816 + ch, g0);
;             if (i < 2) { stf8(ep.f1 + ((size_t)mt * 2 + i) * 2816 + ch, g0); stf8(ep.f2 + ((size_t)mt * 2 + i) * 2816 + ch, up); }
;             if (pos >= len - 2) {
;                 float* so = sq < 4 ? ep.out + O_PFF + (((size_t)ep.layer * 4 + sq) * 2 + (pos - (len - 2))) * 2816
;                                    : ep.out + O_SFF + (((size_t)ep.layer * 8 + (sq - 4)) * 2 + (pos - (len - 2))) * 2816;
;                 stf8(so + ch, g0);
;             }
;             if (i < 2 && defer01) continue;
;             F8 g1, g2;
;             const float* hist = sq >= 4 ? ep.c1 + ((size_t)ep.layer * 8 + (sq - 4)) * 2 * 2816 + ch : nullptr;
;             if (pos >= 1) g1 = ldf8(Cs + (i - 1) * LDC + c8);
;             else if (hist) g1 = ldf8(hist + 2816);
;             else { for (int e = 0; e < 8; ++e) g1.v[e] = 0.f; }
;             if (pos >= 2) g2 = ldf8(Cs + (i - 2) * LDC + c8);
;             else if (hist) g2 = ldf8(hist + (size_t)pos * 2816);
;             else { for (int e = 0; e < 8; ++e) g2.v[e] = 0.f; }
;             F8 o;
; #pragma unroll
;             for (int e = 0; e < 8; ++e) o.v[e] = siluf(w0.v[e] * g2.v[e] + w1.v[e] * g1.v[e] + w2.v[e] * g0.v[e]) * up.v[e];
;             stb8(ep.b0 + (size_t)r * 2816 + ch, o);
; template <int MODE>
; DI void gemm_phase(const bf16_t* __restrict__ A, const bf16_t* __restrict__ Bt, int M, int N, int K, const Epi& ep) {
;     ...
;         for (int ai = 0; ai < 2; ++ai)
; #pragma unroll
;             for (int bj = 0; bj < 2; ++bj) {
; #pragma unroll
;                 for (int m = 0; m < 4; ++m)
; #pragma unroll
;                     for (int n = 0; n < 2; ++n)
;                         *(f32x4*)(Cs + (wr * 64 + m * 16 + fr) * LDC + wc * 32 + n * 16 + fq * 4) = acc[ai][bj][m][n];
;                 __syncthreads();
.Lffn_f2:
	s_mov_b64 exec, -1
	s_waitcnt lgkmcnt(0)
	v_pk_mul_f32 v[120:121], v[128:129], v[120:121]
	v_pk_mul_f32 v[122:123], v[130:131], v[122:123]
	v_pk_mul_f32 v[124:125], v[132:133], v[124:125]
	v_pk_mul_f32 v[126:127], v[134:135], v[126:127]
	v_pk_fma_f32 v[120:121], v[136:137], v[112:113], v[120:121]
	v_pk_fma_f32 v[122:123], v[138:139], v[114:115], v[122:123]
	v_pk_fma_f32 v[124:125], v[140:141], v[116:117], v[124:125]
	v_pk_fma_f32 v[126:127], v[142:143], v[118:119], v[126:127]
	v_pk_fma_f32 v[120:121], v[144:145], v[96:97], v[120:121]
	v_pk_fma_f32 v[122:123], v[146:147], v[98:99], v[122:123]
	v_pk_fma_f32 v[124:125], v[148:149], v[100:101], v[124:125]
	v_pk_fma_f32 v[126:127], v[150:151], v[102:103], v[126:127]
	v_pk_mul_f32 v[152:153], v[120:121], s[30:31]
	v_pk_mul_f32 v[154:155], v[122:123], s[30:31]
	v_pk_mul_f32 v[164:165], v[124:125], s[30:31]
	v_pk_mul_f32 v[166:167], v[126:127], s[30:31]
	v_pk_mul_f32 v[120:121], v[104:105], v[120:121]
	v_pk_mul_f32 v[122:123], v[106:107], v[122:123]
	v_pk_mul_f32 v[124:125], v[108:109], v[124:125]
	v_pk_mul_f32 v[126:127], v[110:111], v[126:127]
	v_exp_f32_e32 v152, v152
	v_exp_f32_e32 v153, v153
	v_exp_f32_e32 v154, v154
	v_exp_f32_e32 v155, v155
	v_exp_f32_e32 v164, v164
	v_exp_f32_e32 v165, v165
	v_exp_f32_e32 v166, v166
	v_exp_f32_e32 v167, v167
	v_pk_add_f32 v[152:153], v[152:153], 1.0 op_sel_hi:[1,0]
	v_pk_add_f32 v[154:155], v[154:155], 1.0 op_sel_hi:[1,0]
	v_pk_add_f32 v[164:165], v[164:165], 1.0 op_sel_hi:[1,0]
	v_pk_add_f32 v[166:167], v[166:167], 1.0 op_sel_hi:[1,0]
	v_rcp_f32_e32 v152, v152
	v_rcp_f32_e32 v153, v153
	v_rcp_f32_e32 v154, v154
	v_rcp_f32_e32 v155, v155
	v_rcp_f32_e32 v164, v164
	v_rcp_f32_e32 v165, v165
	v_rcp_f32_e32 v166, v166
	v_rcp_f32_e32 v167, v167
	v_pk_mul_f32 v[120:121], v[120:121], v[152:153]
	v_pk_mul_f32 v[122:123], v[122:123], v[154:155]
	v_pk_mul_f32 v[124:125], v[124:125], v[164:165]
	v_pk_mul_f32 v[126:127], v[126:127], v[166:167]
	v_cvt_pk_bf16_f32 v152, v120, v121
	v_cvt_pk_bf16_f32 v153, v122, v123
	v_cvt_pk_bf16_f32 v154, v124, v125
	v_cvt_pk_bf16_f32 v155, v126, v127
	global_store_dwordx4 v67, v[152:155], s[84:85] offset:0
	global_load_dwordx4 v[128:131], v64, s[6:7] offset:256
	global_load_dwordx4 v[132:135], v64, s[6:7] offset:272
	global_load_dwordx4 v[136:139], v64, s[14:15] offset:256
	global_load_dwordx4 v[140:143], v64, s[14:15] offset:272
	global_load_dwordx4 v[144:147], v64, s[18:19] offset:256
	global_load_dwordx4 v[148:151], v64, s[18:19] offset:272
	ds_write_b128 v156, v[222:225]
	ds_write_b128 v156, v[68:71] offset:64
	ds_write_b128 v156, v[72:75] offset:8448
	ds_write_b128 v156, v[76:79] offset:8512
	ds_write_b128 v156, v[80:83] offset:16896
	ds_write_b128 v156, v[84:87] offset:16960
	ds_write_b128 v156, v[88:91] offset:25344
	ds_write_b128 v156, v[92:95] offset:25408
	s_waitcnt lgkmcnt(0)
	s_barrier
	ds_read_b128 v[96:99], v158
	ds_read_b128 v[100:103], v158 offset:16
	ds_read_b128 v[104:107], v158 offset:256
	ds_read_b128 v[108:111], v158 offset:272
	ds_read_b128 v[112:115], v157 offset:528
	ds_read_b128 v[116:119], v157 offset:544
	ds_read_b128 v[120:123], v157
	ds_read_b128 v[124:127], v157 offset:16
	s_waitcnt vmcnt(0)
	s_mov_b64 exec, s[42:43]
	s_cbranch_execz .Lffn_f3
	s_waitcnt lgkmcnt(4)
	global_store_dwordx4 v66, v[96:99], s[80:81] offset:256
	global_store_dwordx4 v66, v[100:103], s[80:81] offset:272
	global_store_dwordx4 v66, v[104:107], s[82:83] offset:256
	global_store_dwordx4 v66, v[108:111], s[82:83] offset:272

; template <int MODE>
; DI void gemm_epilogue(const float* Cs, int m0, int n0, const Epi& ep) {
;     ...
;         const F8 w0 = ldf8(cw + ch), w1 = ldf8(cw + 2816 + ch), w2 = ldf8(cw + 2 * 2816 + ch);
;         const bool defer01 = (m0 < MP) && ((m0 & 8191) != 0);
; #pragma unroll
;         for (int it = 0; it < 2; ++it) {
;             const int i = (tid >> 3) + 64 * it, r = m0 + i;
;             int sq, pos, len; rowinfo(r, sq, pos, len);
;             const F8 g0 = ldf8(Cs + i * LDC + c8), up = ldf8(Cs + i * LDC + 64 + c8);
;             if (i >= 126) stf8(ep.f0 + ((size_t)mt * 2 + (i - 126)) * 2816 + ch, g0);
;             if (i < 2) { stf8(ep.f1 + ((size_t)mt * 2 + i) * 2816 + ch, g0); stf8(ep.f2 + ((size_t)mt * 2 + i) * 2816 + ch, up); }
;             if (pos >= len - 2) {
;                 float* so = sq < 4 ? ep.out + O_PFF + (((size_t)ep.layer * 4 + sq) * 2 + (pos - (len - 2))) * 2816
;                                    : ep.out + O_SFF + (((size_t)ep.layer * 8 + (sq - 4)) * 2 + (pos - (len - 2))) * 2816;
;                 stf8(so + ch, g0);
;             }
;             if (i < 2 && defer01) continue;
;             F8 g1, g2;
;             const float* hist = sq >= 4 ? ep.c1 + ((size_t)ep.layer * 8 + (sq - 4)) * 2 * 2816 + ch : nullptr;
;             if (pos >= 1) g1 = ldf8(Cs + (i - 1) * LDC + c8);
;             else if (hist) g1 = ldf8(hist + 2816);
;             else { for (int e = 0; e < 8; ++e) g1.v[e] = 0.f; }
;             if (pos >= 2) g2 = ldf8(Cs + (i - 2) * LDC + c8);
;             else if (hist) g2 = ldf8(hist + (size_t)pos * 2816);
;             else { for (int e = 0; e < 8; ++e) g2.v[e] = 0.f; }
;             F8 o;
; #pragma unroll
;             for (int e = 0; e < 8; ++e) o.v[e] = siluf(w0.v[e] * g2.v[e] + w1.v[e] * g1.v[e] + w2.v[e] * g0.v[e]) * up.v[e];
;             stb8(ep.b0 + (size_t)r * 2816 + ch, o);
; template <int MODE>
; DI void gemm_phase(const bf16_t* __restrict__ A, const bf16_t* __restrict__ Bt, int M, int N, int K, const Epi& ep) {
;     ...
;         for (int ai = 0; ai < 2; ++ai)
; #pragma unroll
;             for (int bj = 0; bj < 2; ++bj) {
; #pragma unroll
;                 for (int m = 0; m < 4; ++m)
; #pragma unroll
;                     for (int n = 0; n < 2; ++n)
;                         *(f32x4*)(Cs + (wr * 64 + m * 16 + fr) * LDC + wc * 32 + n * 16 + fq * 4) = acc[ai][bj][m][n];
;                 __syncthreads();
.Lffn_f4:
	s_mov_b64 exec, -1
	s_waitcnt lgkmcnt(0)
	v_pk_mul_f32 v[120:121], v[128:129], v[120:121]
	v_pk_mul_f32 v[122:123], v[130:131], v[122:123]
	v_pk_mul_f32 v[124:125], v[132:133], v[124:125]
	v_pk_mul_f32 v[126:127], v[134:135], v[126:127]
	v_pk_fma_f32 v[120:121], v[136:137], v[112:113], v[120:121]
	v_pk_fma_f32 v[122:123], v[138:139], v[114:115], v[122:123]
	v_pk_fma_f32 v[124:125], v[140:141], v[116:117], v[124:125]
	v_pk_fma_f32 v[126:127], v[142:143], v[118:119], v[126:127]
	v_pk_fma_f32 v[120:121], v[144:145], v[96:97], v[120:121]
	v_pk_fma_f32 v[122:123], v[146:147], v[98:99], v[122:123]
	v_pk_fma_f32 v[124:125], v[148:149], v[100:101], v[124:125]
	v_pk_fma_f32 v[126:127], v[150:151], v[102:103], v[126:127]
	v_pk_mul_f32 v[152:153], v[120:121], s[30:31]
	v_pk_mul_f32 v[154:155], v[122:123], s[30:31]
	v_pk_mul_f32 v[164:165], v[124:125], s[30:31]
	v_pk_mul_f32 v[166:167], v[126:127], s[30:31]
	v_pk_mul_f32 v[120:121], v[104:105], v[120:121]
	v_pk_mul_f32 v[122:123], v[106:107], v[122:123]
	v_pk_mul_f32 v[124:125], v[108:109], v[124:125]
	v_pk_mul_f32 v[126:127], v[110:111], v[126:127]
	v_exp_f32_e32 v152, v152
	v_exp_f32_e32 v153, v153
	v_exp_f32_e32 v154, v154
	v_exp_f32_e32 v155, v155
	v_exp_f32_e32 v164, v164
	v_exp_f32_e32 v165, v165
	v_exp_f32_e32 v166, v166
	v_exp_f32_e32 v167, v167
	v_pk_add_f32 v[152:153], v[152:153], 1.0 op_sel_hi:[1,0]
	v_pk_add_f32 v[154:155], v[154:155], 1.0 op_sel_hi:[1,0]
	v_pk_add_f32 v[164:165], v[164:165], 1.0 op_sel_hi:[1,0]
	v_pk_add_f32 v[166:167], v[166:167], 1.0 op_sel_hi:[1,0]
	v_rcp_f32_e32 v152, v152
	v_rcp_f32_e32 v153, v153
	v_rcp_f32_e32 v154, v154
	v_rcp_f32_e32 v155, v155
	v_rcp_f32_e32 v164, v164
	v_rcp_f32_e32 v165, v165
	v_rcp_f32_e32 v166, v166
	v_rcp_f32_e32 v167, v167
	v_pk_mul_f32 v[120:121], v[120:121], v[152:153]
	v_pk_mul_f32 v[122:123], v[122:123], v[154:155]
	v_pk_mul_f32 v[124:125], v[124:125], v[164:165]
	v_pk_mul_f32 v[126:127], v[126:127], v[166:167]
	v_cvt_pk_bf16_f32 v152, v120, v121
	v_cvt_pk_bf16_f32 v153, v122, v123
	v_cvt_pk_bf16_f32 v154, v124, v125
	v_cvt_pk_bf16_f32 v155, v126, v127
	global_store_dwordx4 v67, v[152:155], s[84:85] offset:128
	global_load_dwordx4 v[128:131], v64, s[6:7] offset:0
	global_load_dwordx4 v[132:135], v64, s[6:7] offset:16
	global_load_dwordx4 v[136:139], v64, s[14:15] offset:0
	global_load_dwordx4 v[140:143], v64, s[14:15] offset:16
	global_load_dwordx4 v[144:147], v64, s[18:19] offset:0
	global_load_dwordx4 v[148:151], v64, s[18:19] offset:16
	ds_write_b128 v194, v[32:35]
	ds_write_b128 v194, v[36:39] offset:64
	ds_write_b128 v194, v[40:43] offset:8448
	ds_write_b128 v194, v[44:47] offset:8512
	ds_write_b128 v194, v[48:51] offset:16896
	ds_write_b128 v194, v[52:55] offset:16960
	ds_write_b128 v194, v[56:59] offset:25344
	ds_write_b128 v194, v[60:63] offset:25408
	s_waitcnt lgkmcnt(0)
	s_barrier
	ds_read_b128 v[96:99], v197
	ds_read_b128 v[100:103], v197 offset:16
	ds_read_b128 v[104:107], v197 offset:256
	ds_read_b128 v[108:111], v197 offset:272
	ds_read_b128 v[112:115], v196 offset:528
	ds_read_b128 v[116:119], v196 offset:544
	ds_read_b128 v[120:123], v196
	ds_read_b128 v[124:127], v196 offset:16
	v_add_u32_e32 v67, 0xb0000, v65
	s_waitcnt vmcnt(0)
	s_mov_b64 exec, s[42:43]
	s_cbranch_execz .Lffn_f5
	v_add_u32_e32 v212, 0x5800, v66
	s_waitcnt lgkmcnt(4)
	global_store_dwordx4 v212, v[96:99], s[80:81] offset:0
	global_store_dwordx4 v212, v[100:103], s[80:81] offset:16
	global_store_dwordx4 v212, v[104:107], s[82:83] offset:0
	global_store_dwordx4 v212, v[108:111], s[82:83] offset:16

; template <int MODE>
; DI void gemm_epilogue(const float* Cs, int m0, int n0, const Epi& ep) {
;     ...
;         const F8 w0 = ldf8(cw + ch), w1 = ldf8(cw + 2816 + ch), w2 = ldf8(cw + 2 * 2816 + ch);
;         const bool defer01 = (m0 < MP) && ((m0 & 8191) != 0);
; #pragma unroll
;         for (int it = 0; it < 2; ++it) {
;             const int i = (tid >> 3) + 64 * it, r = m0 + i;
;             int sq, pos, len; rowinfo(r, sq, pos, len);
;             const F8 g0 = ldf8(Cs + i * LDC + c8), up = ldf8(Cs + i * LDC + 64 + c8);
;             if (i >= 126) stf8(ep.f0 + ((size_t)mt * 2 + (i - 126)) * 2816 + ch, g0);
;             if (i < 2) { stf8(ep.f1 + ((size_t)mt * 2 + i) * 2816 + ch, g0); stf8(ep.f2 + ((size_t)mt * 2 + i) * 2816 + ch, up); }
;             if (pos >= len - 2) {
;                 float* so = sq < 4 ? ep.out + O_PFF + (((size_t)ep.layer * 4 + sq) * 2 + (pos - (len - 2))) * 2816
;                                    : ep.out + O_SFF + (((size_t)ep.layer * 8 + (sq - 4)) * 2 + (pos - (len - 2))) * 2816;
;                 stf8(so + ch, g0);
;             }
;             if (i < 2 && defer01) continue;
;             F8 g1, g2;
;             const float* hist = sq >= 4 ? ep.c1 + ((size_t)ep.layer * 8 + (sq - 4)) * 2 * 2816 + ch : nullptr;
;             if (pos >= 1) g1 = ldf8(Cs + (i - 1) * LDC + c8);
;             else if (hist) g1 = ldf8(hist + 2816);
;             else { for (int e = 0; e < 8; ++e) g1.v[e] = 0.f; }
;             if (pos >= 2) g2 = ldf8(Cs + (i - 2) * LDC + c8);
;             else if (hist) g2 = ldf8(hist + (size_t)pos * 2816);
;             else { for (int e = 0; e < 8; ++e) g2.v[e] = 0.f; }
;             F8 o;
; #pragma unroll
;             for (int e = 0; e < 8; ++e) o.v[e] = siluf(w0.v[e] * g2.v[e] + w1.v[e] * g1.v[e] + w2.v[e] * g0.v[e]) * up.v[e];
;             stb8(ep.b0 + (size_t)r * 2816 + ch, o);
; template <int MODE>
; DI void gemm_phase(const bf16_t* __restrict__ A, const bf16_t* __restrict__ Bt, int M, int N, int K, const Epi& ep) {
;     ...
;         for (int ai = 0; ai < 2; ++ai)
; #pragma unroll
;             for (int bj = 0; bj < 2; ++bj) {
; #pragma unroll
;                 for (int m = 0; m < 4; ++m)
; #pragma unroll
;                     for (int n = 0; n < 2; ++n)
;                         *(f32x4*)(Cs + (wr * 64 + m * 16 + fr) * LDC + wc * 32 + n * 16 + fq * 4) = acc[ai][bj][m][n];
;                 __syncthreads();
.Lffn_f6:
	s_mov_b64 exec, -1
	s_waitcnt lgkmcnt(0)
	v_pk_mul_f32 v[120:121], v[128:129], v[120:121]
	v_pk_mul_f32 v[122:123], v[130:131], v[122:123]
	v_pk_mul_f32 v[124:125], v[132:133], v[124:125]
	v_pk_mul_f32 v[126:127], v[134:135], v[126:127]
	v_pk_fma_f32 v[120:121], v[136:137], v[112:113], v[120:121]
	v_pk_fma_f32 v[122:123], v[138:139], v[114:115], v[122:123]
	v_pk_fma_f32 v[124:125], v[140:141], v[116:117], v[124:125]
	v_pk_fma_f32 v[126:127], v[142:143], v[118:119], v[126:127]
	v_pk_fma_f32 v[120:121], v[144:145], v[96:97], v[120:121]
	v_pk_fma_f32 v[122:123], v[146:147], v[98:99], v[122:123]
	v_pk_fma_f32 v[124:125], v[148:149], v[100:101], v[124:125]
	v_pk_fma_f32 v[126:127], v[150:151], v[102:103], v[126:127]
	v_pk_mul_f32 v[152:153], v[120:121], s[30:31]
	v_pk_mul_f32 v[154:155], v[122:123], s[30:31]
	v_pk_mul_f32 v[164:165], v[124:125], s[30:31]
	v_pk_mul_f32 v[166:167], v[126:127], s[30:31]
	v_pk_mul_f32 v[120:121], v[104:105], v[120:121]
	v_pk_mul_f32 v[122:123], v[106:107], v[122:123]
	v_pk_mul_f32 v[124:125], v[108:109], v[124:125]
	v_pk_mul_f32 v[126:127], v[110:111], v[126:127]
	v_exp_f32_e32 v152, v152
	v_exp_f32_e32 v153, v153
	v_exp_f32_e32 v154, v154
	v_exp_f32_e32 v155, v155
	v_exp_f32_e32 v164, v164
	v_exp_f32_e32 v165, v165
	v_exp_f32_e32 v166, v166
	v_exp_f32_e32 v167, v167
	v_pk_add_f32 v[152:153], v[152:153], 1.0 op_sel_hi:[1,0]
	v_pk_add_f32 v[154:155], v[154:155], 1.0 op_sel_hi:[1,0]
	v_pk_add_f32 v[164:165], v[164:165], 1.0 op_sel_hi:[1,0]
	v_pk_add_f32 v[166:167], v[166:167], 1.0 op_sel_hi:[1,0]
	v_rcp_f32_e32 v152, v152
	v_rcp_f32_e32 v153, v153
	v_rcp_f32_e32 v154, v154
	v_rcp_f32_e32 v155, v155
	v_rcp_f32_e32 v164, v164
	v_rcp_f32_e32 v165, v165
	v_rcp_f32_e32 v166, v166
	v_rcp_f32_e32 v167, v167
	v_pk_mul_f32 v[120:121], v[120:121], v[152:153]
	v_pk_mul_f32 v[122:123], v[122:123], v[154:155]
	v_pk_mul_f32 v[124:125], v[124:125], v[164:165]
	v_pk_mul_f32 v[126:127], v[126:127], v[166:167]
	v_cvt_pk_bf16_f32 v152, v120, v121
	v_cvt_pk_bf16_f32 v153, v122, v123
	v_cvt_pk_bf16_f32 v154, v124, v125
	v_cvt_pk_bf16_f32 v155, v126, v127
	global_store_dwordx4 v67, v[152:155], s[84:85] offset:0
	global_load_dwordx4 v[128:131], v64, s[6:7] offset:256
	global_load_dwordx4 v[132:135], v64, s[6:7] offset:272
	global_load_dwordx4 v[136:139], v64, s[14:15] offset:256
	global_load_dwordx4 v[140:143], v64, s[14:15] offset:272
	global_load_dwordx4 v[144:147], v64, s[18:19] offset:256
	global_load_dwordx4 v[148:151], v64, s[18:19] offset:272
	ds_write_b128 v156, v[0:3]
	ds_write_b128 v156, v[4:7] offset:64
	ds_write_b128 v156, v[8:11] offset:8448
	ds_write_b128 v156, v[12:15] offset:8512
	ds_write_b128 v156, v[16:19] offset:16896
	ds_write_b128 v156, v[20:23] offset:16960
	ds_write_b128 v156, v[24:27] offset:25344
	ds_write_b128 v156, v[28:31] offset:25408
	s_waitcnt lgkmcnt(0)
	s_barrier
	ds_read_b128 v[96:99], v158
	ds_read_b128 v[100:103], v158 offset:16
	ds_read_b128 v[104:107], v158 offset:256
	ds_read_b128 v[108:111], v158 offset:272
	ds_read_b128 v[112:115], v157 offset:528
	ds_read_b128 v[116:119], v157 offset:544
	ds_read_b128 v[120:123], v157
	ds_read_b128 v[124:127], v157 offset:16
	v_add_u32_e32 v67, 0xb0000, v65
	s_waitcnt vmcnt(0)
	s_mov_b64 exec, s[42:43]
	s_cbranch_execz .Lffn_f7
	v_add_u32_e32 v212, 0x5800, v66
	s_waitcnt lgkmcnt(4)
	global_store_dwordx4 v212, v[96:99], s[80:81] offset:256
	global_store_dwordx4 v212, v[100:103], s[80:81] offset:272
	global_store_dwordx4 v212, v[104:107], s[82:83] offset:256
	global_store_dwordx4 v212, v[108:111], s[82:83] offset:272
